# wave_sum butterflies in the rmsnorm-type phases (prologue rstd, normgate, dsa_post): DPP quad_perm/row_mirror adds + permlane16/32 swaps instead of six ds_bpermute round trips each
# speedup vs baseline: 1.0051x; 1.0005x over previous
.LBB0_36:
	v_mov_b32_e32 v114, v67
	v_mov_b32_e32 v115, v71
	v_mov_b32_e32 v118, v69
	v_mov_b32_e32 v119, v73
	v_mov_b32_e32 v112, v66
	v_mov_b32_e32 v113, v70
	v_pk_mul_f32 v[114:115], v[114:115], v[114:115]
	v_mov_b32_e32 v116, v68
	v_mov_b32_e32 v117, v72
	v_pk_mul_f32 v[118:119], v[118:119], v[118:119]
	v_pk_fma_f32 v[112:113], v[112:113], v[112:113], v[114:115]
	v_pk_fma_f32 v[114:115], v[116:117], v[116:117], v[118:119]
	v_pk_mul_f32 v[116:117], v[64:65], v[64:65]
	v_pk_add_f32 v[112:113], v[112:113], v[114:115]
	v_pk_mul_f32 v[114:115], v[62:63], v[62:63]
	v_pk_add_f32 v[112:113], v[112:113], v[112:113] op_sel_hi:[0,1]
	v_mov_b32_e32 v118, v114
	v_mov_b32_e32 v119, v117
	v_pk_mov_b32 v[114:115], v[114:115], v[116:117] op_sel:[1,0]
	v_mul_f32_e32 v112, v58, v58
	v_pk_add_f32 v[114:115], v[114:115], v[118:119]
	v_pk_fma_f32 v[116:117], v[58:59], v[58:59], v[112:113] op_sel_hi:[1,1,0]
	v_mul_f32_e32 v112, v60, v60
	v_pk_add_f32 v[114:115], v[114:115], v[114:115] op_sel_hi:[0,1]
	v_pk_fma_f32 v[118:119], v[60:61], v[60:61], v[112:113] op_sel_hi:[1,1,0]
	v_mul_f32_e32 v116, v54, v54
	v_mul_f32_e32 v118, v55, v55
	v_mul_f32_e32 v114, v56, v56
	v_mul_f32_e32 v112, v57, v57
	v_pk_add_f32 v[116:117], v[116:117], v[118:119]
	v_pk_add_f32 v[112:113], v[114:115], v[112:113]
	v_pk_mul_f32 v[114:115], v[50:51], v[50:51]
	v_pk_add_f32 v[112:113], v[116:117], v[112:113]
	v_pk_mul_f32 v[116:117], v[52:53], v[52:53]
	v_pk_add_f32 v[112:113], v[112:113], v[112:113] op_sel_hi:[0,1]
	v_mov_b32_e32 v118, v114
	v_mov_b32_e32 v119, v117
	v_pk_mov_b32 v[114:115], v[114:115], v[116:117] op_sel:[1,0]
	v_mul_f32_e32 v112, v44, v44
	v_pk_add_f32 v[114:115], v[114:115], v[118:119]
	v_pk_fma_f32 v[116:117], v[44:45], v[44:45], v[112:113] op_sel_hi:[1,1,0]
	v_mul_f32_e32 v112, v48, v48
	v_pk_add_f32 v[114:115], v[114:115], v[114:115] op_sel_hi:[0,1]
	v_pk_fma_f32 v[118:119], v[48:49], v[48:49], v[112:113] op_sel_hi:[1,1,0]
	v_mul_f32_e32 v116, v40, v40
	v_mul_f32_e32 v118, v41, v41
	v_mul_f32_e32 v114, v42, v42
	v_mul_f32_e32 v112, v43, v43
	v_pk_add_f32 v[116:117], v[116:117], v[118:119]
	v_pk_add_f32 v[112:113], v[114:115], v[112:113]
	v_lshl_add_u64 v[46:47], v[46:47], 0, s[34:35]
	v_pk_add_f32 v[112:113], v[116:117], v[112:113]
	s_nop 0
	v_add_f32_e32 v111, v112, v113
	s_nop 1
	v_add_f32_dpp v111, v111, v111 quad_perm:[1,0,3,2] row_mask:0xf bank_mask:0xf
	s_nop 1
	v_add_f32_dpp v111, v111, v111 quad_perm:[2,3,0,1] row_mask:0xf bank_mask:0xf
	s_nop 1
	v_add_f32_dpp v111, v111, v111 row_half_mirror row_mask:0xf bank_mask:0xf
	s_nop 1
	v_add_f32_dpp v111, v111, v111 row_mirror row_mask:0xf bank_mask:0xf
	v_mov_b32_e32 v112, v111
	s_nop 1
	v_permlane16_swap_b32 v112, v111
	v_add_f32_e32 v111, v111, v112
	v_mov_b32_e32 v112, v111
	s_nop 1
	v_permlane32_swap_b32 v112, v111
	v_add_f32_e32 v111, v111, v112
	v_fmamk_f32 v111, v111, 0x3a000000, v167
	v_mul_f32_e32 v112, 0x4f800000, v111
	v_cmp_gt_f32_e32 vcc, s54, v111
	s_nop 1
	v_cndmask_b32_e32 v111, v111, v112, vcc
	v_sqrt_f32_e32 v112, v111
	s_nop 0
	v_add_u32_e32 v113, -1, v112
	v_fma_f32 v114, -v113, v112, v111
	v_cmp_ge_f32_e64 s[0:1], 0, v114
	v_add_u32_e32 v114, 1, v112
	s_nop 0
	v_cndmask_b32_e64 v113, v112, v113, s[0:1]
	v_fma_f32 v112, -v114, v112, v111
	v_cmp_lt_f32_e64 s[0:1], 0, v112
	s_nop 1
	v_cndmask_b32_e64 v112, v113, v114, s[0:1]
	v_mul_f32_e32 v113, 0x37800000, v112
	v_cndmask_b32_e32 v112, v112, v113, vcc
	v_cmp_class_f32_e32 vcc, v111, v171
	s_nop 1
	v_cndmask_b32_e32 v111, v112, v111, vcc
	v_div_scale_f32 v112, s[0:1], v111, v111, 1.0
	v_rcp_f32_e32 v113, v112
	s_nop 0
	v_fma_f32 v114, -v112, v113, 1.0
	v_fmac_f32_e32 v113, v114, v113
	v_div_scale_f32 v114, vcc, 1.0, v111, 1.0
	v_mul_f32_e32 v115, v114, v113
	v_fma_f32 v116, -v112, v115, v114
	v_fmac_f32_e32 v115, v116, v113
	v_fma_f32 v112, -v112, v115, v114
	v_div_fmas_f32 v112, v112, v113, v115
	v_div_fixup_f32 v112, v112, v111, 1.0
	v_pk_mul_f32 v[50:51], v[112:113], v[50:51] op_sel_hi:[0,1]
	v_pk_mul_f32 v[52:53], v[112:113], v[52:53] op_sel_hi:[0,1]
	v_pk_mul_f32 v[70:71], v[112:113], v[70:71] op_sel_hi:[0,1]
	v_pk_mul_f32 v[72:73], v[112:113], v[72:73] op_sel_hi:[0,1]
	v_pk_mul_f32 v[66:67], v[112:113], v[66:67] op_sel_hi:[0,1]
	v_pk_mul_f32 v[68:69], v[112:113], v[68:69] op_sel_hi:[0,1]
	v_pk_mul_f32 v[62:63], v[112:113], v[62:63] op_sel_hi:[0,1]
	v_pk_mul_f32 v[64:65], v[112:113], v[64:65] op_sel_hi:[0,1]
	v_pk_mul_f32 v[58:59], v[112:113], v[58:59] op_sel_hi:[0,1]
	v_pk_mul_f32 v[60:61], v[112:113], v[60:61] op_sel_hi:[0,1]
	v_pk_mul_f32 v[54:55], v[112:113], v[54:55] op_sel_hi:[0,1]
	v_pk_mul_f32 v[56:57], v[112:113], v[56:57] op_sel_hi:[0,1]
	s_waitcnt vmcnt(2)
	v_pk_mul_f32 v[52:53], v[22:23], v[52:53]
	v_pk_mul_f32 v[50:51], v[20:21], v[50:51]
	v_pk_mul_f32 v[44:45], v[112:113], v[44:45] op_sel_hi:[0,1]
	v_pk_mul_f32 v[48:49], v[112:113], v[48:49] op_sel_hi:[0,1]
	v_pk_mul_f32 v[40:41], v[112:113], v[40:41] op_sel_hi:[0,1]
	v_pk_mul_f32 v[42:43], v[112:113], v[42:43] op_sel_hi:[0,1]
	v_pk_mul_f32 v[72:73], v[2:3], v[72:73]
	v_pk_mul_f32 v[70:71], v[0:1], v[70:71]
	v_pk_mul_f32 v[68:69], v[6:7], v[68:69]
	v_pk_mul_f32 v[66:67], v[4:5], v[66:67]
	v_pk_mul_f32 v[64:65], v[10:11], v[64:65]
	v_pk_mul_f32 v[62:63], v[8:9], v[62:63]
	v_pk_mul_f32 v[60:61], v[14:15], v[60:61]
	v_pk_mul_f32 v[58:59], v[12:13], v[58:59]
	v_pk_mul_f32 v[56:57], v[18:19], v[56:57]
	v_pk_mul_f32 v[54:55], v[16:17], v[54:55]
	global_store_dwordx4 v[34:35], v[50:53], off offset:1024
	s_waitcnt vmcnt(1)
	v_pk_mul_f32 v[42:43], v[30:31], v[42:43]
	v_pk_mul_f32 v[40:41], v[28:29], v[40:41]
	v_pk_mul_f32 v[50:51], v[26:27], v[48:49]
	v_pk_mul_f32 v[48:49], v[24:25], v[44:45]
	global_store_dwordx4 v[34:35], v[70:73], off offset:-4096
	global_store_dwordx4 v[34:35], v[66:69], off offset:-3072
	global_store_dwordx4 v[34:35], v[62:65], off offset:-2048
	global_store_dwordx4 v[34:35], v[58:61], off offset:-1024
	global_store_dwordx4 v[34:35], v[54:57], off
	global_store_dwordx4 v[34:35], v[48:51], off offset:2048
	global_store_dwordx4 v[34:35], v[40:43], off offset:3072
	v_lshl_add_u64 v[34:35], v[34:35], 0, s[30:31]
	s_and_b64 vcc, exec, s[36:37]
	v_mov_b32_e32 v40, v107
	v_mov_b32_e32 v41, v108
	v_mov_b32_e32 v42, v109
	v_mov_b32_e32 v43, v110
	v_mov_b32_e32 v44, v103
	v_mov_b32_e32 v45, v104
	v_mov_b32_e32 v48, v105
	v_mov_b32_e32 v49, v106
	v_mov_b32_e32 v50, v99
	v_mov_b32_e32 v51, v100
	v_mov_b32_e32 v52, v101
	v_mov_b32_e32 v53, v102
	v_mov_b32_e32 v54, v95
	v_mov_b32_e32 v55, v96
	v_mov_b32_e32 v56, v97
	v_mov_b32_e32 v57, v98
	v_mov_b32_e32 v58, v91
	v_mov_b32_e32 v59, v92
	v_mov_b32_e32 v60, v93
	v_mov_b32_e32 v61, v94
	v_mov_b32_e32 v62, v87
	v_mov_b32_e32 v63, v88
	v_mov_b32_e32 v64, v89
	v_mov_b32_e32 v65, v90
	v_mov_b32_e32 v66, v83
	v_mov_b32_e32 v67, v84
	v_mov_b32_e32 v68, v85
	v_mov_b32_e32 v69, v86
	v_mov_b32_e32 v70, v79
	v_mov_b32_e32 v71, v80
	v_mov_b32_e32 v72, v81
	v_mov_b32_e32 v73, v82
	s_cbranch_vccnz .LBB0_42

.LBB0_72:
	v_lshlrev_b32_e32 v88, 16, v79
	v_and_b32_e32 v89, 0xffff0000, v79
	v_and_b32_e32 v79, 0xffff0000, v74
	v_mul_f32_e32 v96, 0xbfb8aa3b, v79
	v_lshlrev_b32_e32 v100, 16, v76
	v_and_b32_e32 v101, 0xffff0000, v76
	v_exp_f32_e32 v102, v96
	v_lshlrev_b32_e32 v96, 16, v77
	v_and_b32_e32 v97, 0xffff0000, v77
	v_pk_mul_f32 v[76:77], v[100:101], v[100:101]
	v_pk_mul_f32 v[98:99], v[96:97], v[96:97]
	v_add_f32_e32 v76, v76, v77
	v_lshlrev_b32_e32 v94, 16, v78
	v_and_b32_e32 v95, 0xffff0000, v78
	v_add_f32_e32 v76, v98, v76
	v_lshlrev_b32_e32 v90, 16, v75
	v_and_b32_e32 v91, 0xffff0000, v75
	v_lshlrev_b32_e32 v78, 16, v74
	v_pk_mul_f32 v[74:75], v[94:95], v[94:95]
	v_add_f32_e32 v76, v99, v76
	v_add_f32_e32 v74, v74, v76
	v_pk_mul_f32 v[92:93], v[88:89], v[88:89]
	v_add_f32_e32 v74, v75, v74
	v_add_f32_e32 v74, v92, v74
	v_add_f32_e32 v76, v93, v74
	v_mul_f32_e32 v87, 0xbfb8aa3b, v78
	v_exp_f32_e32 v87, v87
	v_lshlrev_b32_e32 v98, 16, v72
	v_and_b32_e32 v99, 0xffff0000, v72
	v_add_f32_e32 v75, 1.0, v102
	v_add_f32_e32 v74, 1.0, v87
	s_nop 1
	v_add_f32_dpp v87, v76, v76 quad_perm:[1,0,3,2] row_mask:0xf bank_mask:0xf
	v_lshlrev_b32_e32 v76, 16, v73
	v_mul_f32_e32 v77, 0xbfb8aa3b, v76
	v_exp_f32_e32 v93, v77
	v_and_b32_e32 v77, 0xffff0000, v73
	s_nop 1
	v_add_f32_dpp v73, v87, v87 quad_perm:[2,3,0,1] row_mask:0xf bank_mask:0xf
	v_add_f32_e32 v92, 1.0, v93
	v_mul_f32_e32 v93, 0xbfb8aa3b, v77
	v_exp_f32_e32 v93, v93
	v_mul_f32_e32 v102, 0xbfb8aa3b, v99
	s_nop 1
	v_add_f32_dpp v73, v73, v73 row_half_mirror row_mask:0xf bank_mask:0xf
	v_add_f32_e32 v93, 1.0, v93
	v_exp_f32_e32 v102, v102
	v_rcp_f32_e32 v92, v92
	v_rcp_f32_e32 v93, v93
	s_nop 1
	v_add_f32_dpp v72, v73, v73 row_mirror row_mask:0xf bank_mask:0xf
	v_mul_f32_e32 v87, 0xbfb8aa3b, v98
	v_exp_f32_e32 v87, v87
	v_rcp_f32_e32 v74, v74
	v_rcp_f32_e32 v75, v75
	v_mov_b32_e32 v73, v72
	s_nop 1
	v_permlane16_swap_b32 v73, v72
	v_add_f32_e32 v103, v72, v73
	v_add_f32_e32 v72, 1.0, v87
	v_add_f32_e32 v73, 1.0, v102
	v_rcp_f32_e32 v72, v72
	v_rcp_f32_e32 v73, v73
	v_mov_b32_e32 v104, v103
	s_nop 1
	v_permlane32_swap_b32 v104, v103
	v_add_f32_e32 v87, v103, v104
	v_fmamk_f32 v87, v87, 0x3b000000, v167
	v_rsq_f32_e32 v102, v87
	v_mul_f32_e32 v87, 0xbfb8aa3b, v90
	v_pk_mul_f32 v[76:77], v[92:93], v[76:77]
	v_exp_f32_e32 v87, v87
	v_mul_f32_e32 v92, 0xbfb8aa3b, v91
	v_exp_f32_e32 v93, v92
	v_pk_mul_f32 v[74:75], v[74:75], v[78:79]
	v_pk_mul_f32 v[78:79], v[102:103], v[100:101] op_sel_hi:[0,1]
	v_pk_mul_f32 v[72:73], v[72:73], v[98:99]
	v_pk_mul_f32 v[78:79], v[0:1], v[78:79]
	v_add_f32_e32 v87, 1.0, v87
	v_pk_mul_f32 v[72:73], v[72:73], v[78:79]
	v_pk_mul_f32 v[78:79], v[102:103], v[96:97] op_sel_hi:[0,1]
	v_rcp_f32_e32 v92, v87
	v_add_f32_e32 v87, 1.0, v93
	v_pk_mul_f32 v[78:79], v[2:3], v[78:79]
	v_rcp_f32_e32 v93, v87
	v_pk_mul_f32 v[76:77], v[76:77], v[78:79]
	v_pk_mul_f32 v[78:79], v[102:103], v[94:95] op_sel_hi:[0,1]
	v_pk_mul_f32 v[78:79], v[4:5], v[78:79]
	v_lshl_add_u64 v[80:81], s[28:29], 0, v[34:35]
	v_pk_mul_f32 v[74:75], v[74:75], v[78:79]
	v_pk_mul_f32 v[78:79], v[102:103], v[88:89] op_sel_hi:[0,1]
	v_pk_mul_f32 v[78:79], v[6:7], v[78:79]
	v_pk_mul_f32 v[88:89], v[92:93], v[90:91]
	v_cvt_pk_bf16_f32 v72, v72, v73
	v_pk_mul_f32 v[78:79], v[88:89], v[78:79]
	v_cvt_pk_bf16_f32 v73, v76, v77
	v_cvt_pk_bf16_f32 v74, v74, v75
	v_cvt_pk_bf16_f32 v75, v78, v79
	global_store_dwordx4 v[80:81], v[72:75], off offset:-2048
	v_lshlrev_b32_e32 v92, 16, v68
	v_and_b32_e32 v93, 0xffff0000, v68
	v_lshlrev_b32_e32 v72, 16, v71
	v_and_b32_e32 v73, 0xffff0000, v71
	v_and_b32_e32 v71, 0xffff0000, v66
	v_mul_f32_e32 v88, 0xbfb8aa3b, v71
	v_exp_f32_e32 v94, v88
	v_lshlrev_b32_e32 v88, 16, v69
	v_and_b32_e32 v89, 0xffff0000, v69
	v_pk_mul_f32 v[68:69], v[92:93], v[92:93]
	v_pk_mul_f32 v[90:91], v[88:89], v[88:89]
	v_add_f32_e32 v68, v68, v69
	v_lshlrev_b32_e32 v78, 16, v70
	v_and_b32_e32 v79, 0xffff0000, v70
	v_add_f32_e32 v68, v90, v68
	v_lshlrev_b32_e32 v74, 16, v67
	v_and_b32_e32 v75, 0xffff0000, v67
	v_lshlrev_b32_e32 v70, 16, v66
	v_pk_mul_f32 v[66:67], v[78:79], v[78:79]
	v_add_f32_e32 v68, v91, v68
	v_add_f32_e32 v66, v66, v68
	v_pk_mul_f32 v[76:77], v[72:73], v[72:73]
	v_add_f32_e32 v66, v67, v66
	v_add_f32_e32 v66, v76, v66
	v_add_f32_e32 v68, v77, v66
	v_mul_f32_e32 v87, 0xbfb8aa3b, v70
	v_exp_f32_e32 v87, v87
	v_add_f32_e32 v67, 1.0, v94
	v_lshlrev_b32_e32 v90, 16, v64
	s_nop 1
	v_add_f32_dpp v76, v68, v68 quad_perm:[1,0,3,2] row_mask:0xf bank_mask:0xf
	v_lshlrev_b32_e32 v68, 16, v65
	v_mul_f32_e32 v69, 0xbfb8aa3b, v68
	v_add_f32_e32 v66, 1.0, v87
	v_exp_f32_e32 v87, v69
	v_and_b32_e32 v69, 0xffff0000, v65
	s_nop 1
	v_add_f32_dpp v65, v76, v76 quad_perm:[2,3,0,1] row_mask:0xf bank_mask:0xf
	v_and_b32_e32 v91, 0xffff0000, v64
	v_add_f32_e32 v76, 1.0, v87
	v_mul_f32_e32 v87, 0xbfb8aa3b, v69
	v_exp_f32_e32 v87, v87
	s_nop 1
	v_add_f32_dpp v65, v65, v65 row_half_mirror row_mask:0xf bank_mask:0xf
	v_rcp_f32_e32 v76, v76
	v_add_f32_e32 v77, 1.0, v87
	v_mul_f32_e32 v87, 0xbfb8aa3b, v90
	v_exp_f32_e32 v87, v87
	s_nop 1
	v_add_f32_dpp v64, v65, v65 row_mirror row_mask:0xf bank_mask:0xf
	v_mul_f32_e32 v94, 0xbfb8aa3b, v91
	v_exp_f32_e32 v94, v94
	v_rcp_f32_e32 v77, v77
	v_rcp_f32_e32 v66, v66
	v_mov_b32_e32 v65, v64
	s_nop 1
	v_permlane16_swap_b32 v65, v64
	v_add_f32_e32 v95, v64, v65
	v_add_f32_e32 v64, 1.0, v87
	v_rcp_f32_e32 v67, v67
	v_add_f32_e32 v65, 1.0, v94
	v_rcp_f32_e32 v64, v64
	v_mov_b32_e32 v96, v95
	s_nop 1
	v_permlane32_swap_b32 v96, v95
	v_add_f32_e32 v87, v95, v96
	v_fmamk_f32 v87, v87, 0x3b000000, v167
	v_rsq_f32_e32 v94, v87
	v_rcp_f32_e32 v65, v65
	v_pk_mul_f32 v[68:69], v[76:77], v[68:69]
	v_mul_f32_e32 v76, 0xbfb8aa3b, v74
	v_mul_f32_e32 v77, 0xbfb8aa3b, v75
	v_exp_f32_e32 v76, v76
	v_exp_f32_e32 v77, v77
	v_pk_mul_f32 v[66:67], v[66:67], v[70:71]
	v_pk_mul_f32 v[70:71], v[94:95], v[92:93] op_sel_hi:[0,1]
	v_pk_mul_f32 v[64:65], v[64:65], v[90:91]
	v_pk_mul_f32 v[70:71], v[0:1], v[70:71]
	v_add_f32_e32 v76, 1.0, v76
	v_pk_mul_f32 v[64:65], v[64:65], v[70:71]
	v_pk_mul_f32 v[70:71], v[94:95], v[88:89] op_sel_hi:[0,1]
	v_add_f32_e32 v77, 1.0, v77
	v_pk_mul_f32 v[70:71], v[2:3], v[70:71]
	v_rcp_f32_e32 v76, v76
	v_rcp_f32_e32 v77, v77
	v_pk_mul_f32 v[68:69], v[68:69], v[70:71]
	v_pk_mul_f32 v[70:71], v[94:95], v[78:79] op_sel_hi:[0,1]
	v_pk_mul_f32 v[70:71], v[4:5], v[70:71]
	v_cvt_pk_bf16_f32 v64, v64, v65
	v_pk_mul_f32 v[66:67], v[66:67], v[70:71]
	v_pk_mul_f32 v[70:71], v[94:95], v[72:73] op_sel_hi:[0,1]
	v_pk_mul_f32 v[70:71], v[6:7], v[70:71]
	v_pk_mul_f32 v[72:73], v[76:77], v[74:75]
	v_cvt_pk_bf16_f32 v65, v68, v69
	v_pk_mul_f32 v[70:71], v[72:73], v[70:71]
	v_cvt_pk_bf16_f32 v66, v66, v67
	v_cvt_pk_bf16_f32 v67, v70, v71
	v_lshlrev_b32_e32 v70, 16, v46
	v_and_b32_e32 v71, 0xffff0000, v46
	v_lshlrev_b32_e32 v46, 16, v18
	global_store_dwordx4 v[80:81], v[64:67], off offset:-1024
	v_mul_f32_e32 v72, 0xbfb8aa3b, v46
	v_exp_f32_e32 v78, v72
	v_lshlrev_b32_e32 v64, 16, v47
	v_and_b32_e32 v65, 0xffff0000, v47
	v_and_b32_e32 v47, 0xffff0000, v18
	v_mul_f32_e32 v72, 0xbfb8aa3b, v47
	v_lshlrev_b32_e32 v76, 16, v44
	v_and_b32_e32 v77, 0xffff0000, v44
	v_exp_f32_e32 v79, v72
	v_lshlrev_b32_e32 v72, 16, v45
	v_and_b32_e32 v73, 0xffff0000, v45
	v_pk_mul_f32 v[44:45], v[76:77], v[76:77]
	v_pk_mul_f32 v[74:75], v[72:73], v[72:73]
	v_add_f32_e32 v44, v44, v45
	v_add_f32_e32 v44, v74, v44
	v_lshlrev_b32_e32 v66, 16, v19
	v_and_b32_e32 v67, 0xffff0000, v19
	v_pk_mul_f32 v[18:19], v[70:71], v[70:71]
	v_add_f32_e32 v44, v75, v44
	v_add_f32_e32 v18, v18, v44
	v_pk_mul_f32 v[68:69], v[64:65], v[64:65]
	v_add_f32_e32 v18, v19, v18
	v_add_f32_e32 v18, v68, v18
	v_add_f32_e32 v44, v69, v18
	v_add_f32_e32 v18, 1.0, v78
	v_and_b32_e32 v75, 0xffff0000, v16
	v_add_f32_e32 v19, 1.0, v79
	v_mul_f32_e32 v79, 0xbfb8aa3b, v75
	s_nop 1
	v_add_f32_dpp v68, v44, v44 quad_perm:[1,0,3,2] row_mask:0xf bank_mask:0xf
	v_lshlrev_b32_e32 v44, 16, v17
	v_mul_f32_e32 v45, 0xbfb8aa3b, v44
	v_exp_f32_e32 v74, v45
	v_and_b32_e32 v45, 0xffff0000, v17
	s_nop 1
	v_add_f32_dpp v17, v68, v68 quad_perm:[2,3,0,1] row_mask:0xf bank_mask:0xf
	v_add_f32_e32 v68, 1.0, v74
	v_mul_f32_e32 v74, 0xbfb8aa3b, v45
	v_exp_f32_e32 v74, v74
	v_exp_f32_e32 v79, v79
	s_nop 1
	v_add_f32_dpp v17, v17, v17 row_half_mirror row_mask:0xf bank_mask:0xf
	v_add_f32_e32 v69, 1.0, v74
	v_lshlrev_b32_e32 v74, 16, v16
	v_rcp_f32_e32 v68, v68
	v_rcp_f32_e32 v69, v69
	s_nop 1
	v_add_f32_dpp v16, v17, v17 row_mirror row_mask:0xf bank_mask:0xf
	v_mul_f32_e32 v78, 0xbfb8aa3b, v74
	v_exp_f32_e32 v78, v78
	v_rcp_f32_e32 v18, v18
	v_rcp_f32_e32 v19, v19
	v_mov_b32_e32 v17, v16
	s_nop 1
	v_permlane16_swap_b32 v17, v16
	v_add_f32_e32 v87, v16, v17
	v_add_f32_e32 v16, 1.0, v78
	v_add_f32_e32 v17, 1.0, v79
	v_rcp_f32_e32 v16, v16
	v_rcp_f32_e32 v17, v17
	v_mov_b32_e32 v88, v87
	s_nop 1
	v_permlane32_swap_b32 v88, v87
	v_add_f32_e32 v78, v87, v88
	v_fmamk_f32 v78, v78, 0x3b000000, v167
	v_rsq_f32_e32 v78, v78
	v_pk_mul_f32 v[44:45], v[68:69], v[44:45]
	v_mul_f32_e32 v68, 0xbfb8aa3b, v66
	v_mul_f32_e32 v69, 0xbfb8aa3b, v67
	v_exp_f32_e32 v68, v68
	v_exp_f32_e32 v69, v69
	v_pk_mul_f32 v[18:19], v[18:19], v[46:47]
	v_pk_mul_f32 v[46:47], v[78:79], v[76:77] op_sel_hi:[0,1]
	v_pk_mul_f32 v[16:17], v[16:17], v[74:75]
	v_pk_mul_f32 v[46:47], v[0:1], v[46:47]
	v_add_f32_e32 v68, 1.0, v68
	v_pk_mul_f32 v[16:17], v[16:17], v[46:47]
	v_pk_mul_f32 v[46:47], v[78:79], v[72:73] op_sel_hi:[0,1]
	v_add_f32_e32 v69, 1.0, v69
	v_pk_mul_f32 v[46:47], v[2:3], v[46:47]
	v_rcp_f32_e32 v68, v68
	v_rcp_f32_e32 v69, v69
	v_pk_mul_f32 v[44:45], v[44:45], v[46:47]
	v_pk_mul_f32 v[46:47], v[78:79], v[70:71] op_sel_hi:[0,1]
	v_pk_mul_f32 v[46:47], v[4:5], v[46:47]
	v_cvt_pk_bf16_f32 v16, v16, v17
	v_pk_mul_f32 v[18:19], v[18:19], v[46:47]
	v_pk_mul_f32 v[46:47], v[78:79], v[64:65] op_sel_hi:[0,1]
	v_pk_mul_f32 v[46:47], v[6:7], v[46:47]
	v_pk_mul_f32 v[64:65], v[68:69], v[66:67]
	v_cvt_pk_bf16_f32 v17, v44, v45
	v_pk_mul_f32 v[46:47], v[64:65], v[46:47]
	v_cvt_pk_bf16_f32 v18, v18, v19
	v_cvt_pk_bf16_f32 v19, v46, v47
	v_lshlrev_b32_e32 v46, 16, v14
	v_and_b32_e32 v47, 0xffff0000, v14
	v_lshlrev_b32_e32 v14, 16, v10
	global_store_dwordx4 v[80:81], v[16:19], off
	v_mul_f32_e32 v64, 0xbfb8aa3b, v14
	v_exp_f32_e32 v70, v64
	v_lshlrev_b32_e32 v16, 16, v15
	v_and_b32_e32 v17, 0xffff0000, v15
	v_and_b32_e32 v15, 0xffff0000, v10
	v_mul_f32_e32 v64, 0xbfb8aa3b, v15
	v_lshlrev_b32_e32 v68, 16, v12
	v_and_b32_e32 v69, 0xffff0000, v12
	v_exp_f32_e32 v71, v64
	v_lshlrev_b32_e32 v64, 16, v13
	v_and_b32_e32 v65, 0xffff0000, v13
	v_pk_mul_f32 v[12:13], v[68:69], v[68:69]
	v_pk_mul_f32 v[66:67], v[64:65], v[64:65]
	v_add_f32_e32 v12, v12, v13
	v_add_f32_e32 v12, v66, v12
	v_lshlrev_b32_e32 v18, 16, v11
	v_and_b32_e32 v19, 0xffff0000, v11
	v_pk_mul_f32 v[10:11], v[46:47], v[46:47]
	v_add_f32_e32 v12, v67, v12
	v_add_f32_e32 v10, v10, v12
	v_pk_mul_f32 v[44:45], v[16:17], v[16:17]
	v_add_f32_e32 v10, v11, v10
	v_add_f32_e32 v10, v44, v10
	v_add_f32_e32 v12, v45, v10
	v_add_f32_e32 v10, 1.0, v70
	v_and_b32_e32 v67, 0xffff0000, v8
	v_add_f32_e32 v11, 1.0, v71
	v_mul_f32_e32 v71, 0xbfb8aa3b, v67
	s_nop 1
	v_add_f32_dpp v44, v12, v12 quad_perm:[1,0,3,2] row_mask:0xf bank_mask:0xf
	v_lshlrev_b32_e32 v12, 16, v9
	v_mul_f32_e32 v13, 0xbfb8aa3b, v12
	v_exp_f32_e32 v66, v13
	v_and_b32_e32 v13, 0xffff0000, v9
	s_nop 1
	v_add_f32_dpp v9, v44, v44 quad_perm:[2,3,0,1] row_mask:0xf bank_mask:0xf
	v_add_f32_e32 v44, 1.0, v66
	v_mul_f32_e32 v66, 0xbfb8aa3b, v13
	v_exp_f32_e32 v66, v66
	v_exp_f32_e32 v71, v71
	s_nop 1
	v_add_f32_dpp v9, v9, v9 row_half_mirror row_mask:0xf bank_mask:0xf
	v_add_f32_e32 v45, 1.0, v66
	v_lshlrev_b32_e32 v66, 16, v8
	v_rcp_f32_e32 v44, v44
	v_rcp_f32_e32 v45, v45
	s_nop 1
	v_add_f32_dpp v8, v9, v9 row_mirror row_mask:0xf bank_mask:0xf
	v_mul_f32_e32 v70, 0xbfb8aa3b, v66
	v_exp_f32_e32 v70, v70
	v_rcp_f32_e32 v10, v10
	v_rcp_f32_e32 v11, v11
	v_mov_b32_e32 v9, v8
	s_nop 1
	v_permlane16_swap_b32 v9, v8
	v_add_f32_e32 v72, v8, v9
	v_add_f32_e32 v8, 1.0, v70
	v_add_f32_e32 v9, 1.0, v71
	v_rcp_f32_e32 v8, v8
	v_rcp_f32_e32 v9, v9
	v_mov_b32_e32 v73, v72
	s_nop 1
	v_permlane32_swap_b32 v73, v72
	v_add_f32_e32 v70, v72, v73
	v_fmamk_f32 v70, v70, 0x3b000000, v167
	v_rsq_f32_e32 v70, v70
	v_pk_mul_f32 v[12:13], v[44:45], v[12:13]
	v_mul_f32_e32 v44, 0xbfb8aa3b, v18
	v_mul_f32_e32 v45, 0xbfb8aa3b, v19
	v_exp_f32_e32 v44, v44
	v_exp_f32_e32 v45, v45
	v_pk_mul_f32 v[10:11], v[10:11], v[14:15]
	v_pk_mul_f32 v[14:15], v[70:71], v[68:69] op_sel_hi:[0,1]
	v_pk_mul_f32 v[8:9], v[8:9], v[66:67]
	v_pk_mul_f32 v[14:15], v[0:1], v[14:15]
	v_add_f32_e32 v44, 1.0, v44
	v_pk_mul_f32 v[8:9], v[8:9], v[14:15]
	v_pk_mul_f32 v[14:15], v[70:71], v[64:65] op_sel_hi:[0,1]
	v_add_f32_e32 v45, 1.0, v45
	v_pk_mul_f32 v[14:15], v[2:3], v[14:15]
	v_rcp_f32_e32 v44, v44
	v_rcp_f32_e32 v45, v45
	v_pk_mul_f32 v[12:13], v[12:13], v[14:15]
	v_pk_mul_f32 v[14:15], v[70:71], v[46:47] op_sel_hi:[0,1]
	v_pk_mul_f32 v[14:15], v[4:5], v[14:15]
	s_add_u32 s28, s28, s30
	v_pk_mul_f32 v[10:11], v[10:11], v[14:15]
	v_pk_mul_f32 v[14:15], v[70:71], v[16:17] op_sel_hi:[0,1]
	v_pk_mul_f32 v[14:15], v[6:7], v[14:15]
	v_pk_mul_f32 v[16:17], v[44:45], v[18:19]
	s_addc_u32 s29, s29, s31
	v_pk_mul_f32 v[14:15], v[16:17], v[14:15]
	s_add_u32 s34, s34, s30
	v_readlane_b32 s1, v253, 3
	v_cvt_pk_bf16_f32 v8, v8, v9
	v_cvt_pk_bf16_f32 v9, v12, v13
	v_cvt_pk_bf16_f32 v10, v10, v11
	v_cvt_pk_bf16_f32 v11, v14, v15
	s_addc_u32 s35, s35, s31
	s_mul_i32 s1, s1, 0x11000
	global_store_dwordx4 v[80:81], v[8:11], off offset:1024
	s_add_u32 s36, s36, s1
	s_mul_hi_i32 s1, s2, 0x2200
	s_waitcnt vmcnt(9)
	v_mov_b64_e32 v[74:75], v[22:23]
	s_waitcnt vmcnt(8)
	v_mov_b64_e32 v[66:67], v[26:27]
	s_waitcnt vmcnt(5)
	v_mov_b64_e32 v[16:17], v[28:29]
	s_waitcnt vmcnt(4)
	v_mov_b64_e32 v[8:9], v[40:41]
	v_mov_b64_e32 v[78:79], v[50:51]
	v_mov_b64_e32 v[70:71], v[54:55]
	v_mov_b64_e32 v[44:45], v[56:57]
	v_mov_b64_e32 v[12:13], v[60:61]
	s_addc_u32 s37, s37, s1
	s_and_b64 vcc, exec, s[38:39]
	v_mov_b64_e32 v[72:73], v[20:21]
	v_mov_b64_e32 v[64:65], v[24:25]
	v_mov_b64_e32 v[18:19], v[30:31]
	v_mov_b64_e32 v[10:11], v[42:43]
	v_mov_b64_e32 v[76:77], v[48:49]
	v_mov_b64_e32 v[68:69], v[52:53]
	v_mov_b64_e32 v[46:47], v[58:59]
	v_mov_b64_e32 v[14:15], v[62:63]
	s_cbranch_vccnz .LBB0_75

.LBB0_809:
	v_readlane_b32 s4, v253, 4
	v_readlane_b32 s5, v253, 5
	s_nop 1
	v_lshl_add_u64 v[24:25], v[12:13], 0, s[4:5]
	global_load_dwordx2 v[24:25], v[24:25], off
	s_waitcnt vmcnt(0)
	v_and_b32_e32 v27, 0xffff0000, v25
	v_and_b32_e32 v29, 0xffff0000, v24
	v_lshlrev_b32_e32 v26, 16, v25
	v_lshlrev_b32_e32 v28, 16, v24
	v_mov_b32_e32 v30, v29
	v_mov_b32_e32 v31, v27
	v_mov_b32_e32 v24, v28
	v_mov_b32_e32 v25, v26
	v_pk_mul_f32 v[30:31], v[30:31], v[30:31]
	s_nop 0
	v_pk_fma_f32 v[24:25], v[24:25], v[24:25], v[30:31]
	s_nop 0
	v_add_f32_e32 v24, v24, v25
	s_nop 1
	v_add_f32_dpp v24, v24, v24 quad_perm:[1,0,3,2] row_mask:0xf bank_mask:0xf
	s_nop 1
	v_add_f32_dpp v24, v24, v24 quad_perm:[2,3,0,1] row_mask:0xf bank_mask:0xf
	s_nop 1
	v_add_f32_dpp v24, v24, v24 row_half_mirror row_mask:0xf bank_mask:0xf
	s_nop 1
	v_add_f32_dpp v24, v24, v24 row_mirror row_mask:0xf bank_mask:0xf
	v_mov_b32_e32 v25, v24
	s_nop 1
	v_permlane16_swap_b32 v25, v24
	v_add_f32_e32 v24, v24, v25
	v_mov_b32_e32 v25, v24
	s_nop 1
	v_permlane32_swap_b32 v25, v24
	v_add_f32_e32 v24, v24, v25
	v_fmamk_f32 v24, v24, 0x3b800000, v167
	v_cmp_gt_f32_e32 vcc, s54, v24
	v_mul_f32_e32 v25, 0x4f800000, v24
	s_nop 0
	v_cndmask_b32_e32 v24, v24, v25, vcc
	v_sqrt_f32_e32 v25, v24
	s_nop 0
	v_add_u32_e32 v30, -1, v25
	v_fma_f32 v31, -v30, v25, v24
	v_cmp_ge_f32_e64 s[0:1], 0, v31
	v_add_u32_e32 v31, 1, v25
	s_nop 0
	v_cndmask_b32_e64 v30, v25, v30, s[0:1]
	v_fma_f32 v25, -v31, v25, v24
	v_cmp_lt_f32_e64 s[0:1], 0, v25
	s_nop 1
	v_cndmask_b32_e64 v25, v30, v31, s[0:1]
	v_mul_f32_e32 v30, 0x37800000, v25
	v_cndmask_b32_e32 v25, v25, v30, vcc
	v_cmp_class_f32_e32 vcc, v24, v171
	s_nop 1
	v_cndmask_b32_e32 v24, v25, v24, vcc
	v_div_scale_f32 v25, s[0:1], v24, v24, 1.0
	v_rcp_f32_e32 v30, v25
	s_nop 0
	v_fma_f32 v31, -v25, v30, 1.0
	v_fmac_f32_e32 v30, v31, v30
	v_div_scale_f32 v31, vcc, 1.0, v24, 1.0
	v_mul_f32_e32 v33, v31, v30
	v_fma_f32 v34, -v25, v33, v31
	v_fmac_f32_e32 v33, v34, v30
	v_fma_f32 v25, -v25, v33, v31
	v_div_fmas_f32 v25, v25, v30, v33
	v_div_fixup_f32 v24, v25, v24, 1.0
	v_pk_mul_f32 v[28:29], v[24:25], v[28:29] op_sel_hi:[0,1]
	v_pk_mul_f32 v[24:25], v[24:25], v[26:27] op_sel_hi:[0,1]
	v_pk_mul_f32 v[28:29], v[0:1], v[28:29]
	v_pk_mul_f32 v[24:25], v[2:3], v[24:25]
	v_cvt_pk_bf16_f32 v28, v28, v29
	v_cvt_pk_bf16_f32 v29, v24, v25
	v_lshl_add_u64 v[24:25], v[10:11], 0, s[4:5]
	global_store_dwordx2 v[24:25], v[28:29], off
	v_lshl_add_u64 v[24:25], v[14:15], 0, s[4:5]
	global_load_dword v25, v[24:25], off
	s_waitcnt vmcnt(0)
	v_lshlrev_b32_e32 v24, 16, v25
	v_and_b32_e32 v25, 0xffff0000, v25
	v_pk_mul_f32 v[26:27], v[24:25], v[24:25]
	s_nop 0
	v_add_f32_e32 v26, v26, v27
	s_nop 1
	v_add_f32_dpp v26, v26, v26 quad_perm:[1,0,3,2] row_mask:0xf bank_mask:0xf
	s_nop 1
	v_add_f32_dpp v26, v26, v26 quad_perm:[2,3,0,1] row_mask:0xf bank_mask:0xf
	s_nop 1
	v_add_f32_dpp v26, v26, v26 row_half_mirror row_mask:0xf bank_mask:0xf
	s_nop 1
	v_add_f32_dpp v26, v26, v26 row_mirror row_mask:0xf bank_mask:0xf
	v_mov_b32_e32 v27, v26
	s_nop 1
	v_permlane16_swap_b32 v27, v26
	v_add_f32_e32 v26, v26, v27
	v_mov_b32_e32 v27, v26
	s_nop 1
	v_permlane32_swap_b32 v27, v26
	v_add_f32_e32 v26, v26, v27
	v_fmamk_f32 v26, v26, 0x3c000000, v167
	v_cmp_gt_f32_e32 vcc, s54, v26
	v_mul_f32_e32 v27, 0x4f800000, v26
	s_nop 0
	v_cndmask_b32_e32 v26, v26, v27, vcc
	v_sqrt_f32_e32 v27, v26
	s_nop 0
	v_add_u32_e32 v28, -1, v27
	v_fma_f32 v29, -v28, v27, v26
	v_cmp_ge_f32_e64 s[0:1], 0, v29
	v_add_u32_e32 v29, 1, v27
	s_nop 0
	v_cndmask_b32_e64 v28, v27, v28, s[0:1]
	v_fma_f32 v27, -v29, v27, v26
	v_cmp_lt_f32_e64 s[0:1], 0, v27
	s_nop 1
	v_cndmask_b32_e64 v27, v28, v29, s[0:1]
	v_mul_f32_e32 v28, 0x37800000, v27
	v_cndmask_b32_e32 v27, v27, v28, vcc
	v_cmp_class_f32_e32 vcc, v26, v171
	s_nop 1
	v_cndmask_b32_e32 v26, v27, v26, vcc
	v_div_scale_f32 v27, s[0:1], v26, v26, 1.0
	v_rcp_f32_e32 v28, v27
	s_nop 0
	v_fma_f32 v29, -v27, v28, 1.0
	v_fmac_f32_e32 v28, v29, v28
	v_div_scale_f32 v29, vcc, 1.0, v26, 1.0
	v_mul_f32_e32 v30, v29, v28
	v_fma_f32 v31, -v27, v30, v29
	v_fmac_f32_e32 v30, v31, v28
	v_fma_f32 v27, -v27, v30, v29
	v_div_fmas_f32 v27, v27, v28, v30
	v_div_fixup_f32 v26, v27, v26, 1.0
	v_pk_mul_f32 v[24:25], v[26:27], v[24:25] op_sel_hi:[0,1]
	v_pk_mul_f32 v[24:25], v[4:5], v[24:25]
	s_nop 0
	v_cvt_pk_bf16_f32 v26, v24, v25
	v_lshl_add_u64 v[24:25], v[8:9], 0, s[4:5]
	global_store_dword v[24:25], v26, off
	s_and_saveexec_b64 s[0:1], s[2:3]
	s_cbranch_execz .LBB0_808
	v_readlane_b32 s4, v253, 4
	v_readlane_b32 s5, v253, 5
	s_nop 1
	v_lshl_add_u64 v[24:25], v[16:17], 0, s[4:5]
	global_load_ushort v24, v[24:25], off
	s_waitcnt vmcnt(0)
	v_lshlrev_b32_e32 v24, 16, v24
	v_mul_f32_e32 v26, 0x3cb504f3, v24
	v_lshl_add_u64 v[24:25], v[6:7], 0, s[4:5]
	global_store_dword v[24:25], v26, off
	s_branch .LBB0_808
